# static s_setprio 1 for one wave of each SIMD pair during the attention phase
# speedup vs baseline: 1.0116x; 1.0116x over previous
.LBB0_495:
	v_readlane_b32 s0, v253, 20
	v_readlane_b32 s1, v253, 21
	s_mov_b64 s[54:55], s[78:79]
	s_andn2_b64 vcc, exec, s[0:1]
	s_waitcnt lgkmcnt(0)
	s_barrier
	s_cbranch_vccnz .LBB0_783
	s_getreg_b32 s100, hwreg(HW_REG_HW_ID, 0, 1)
	s_cmp_eq_u32 s100, 1
	s_cbranch_scc0 .Lattn_noprio
	s_setprio 1
.Lattn_noprio:
	s_load_dwordx2 s[0:1], s[54:55], 0xd0
	v_writelane_b32 v255, s78, 7
	v_readlane_b32 s4, v253, 56
	v_readlane_b32 s5, v253, 57
	v_writelane_b32 v255, s79, 8
	s_waitcnt lgkmcnt(0)
	s_add_u32 s2, s0, 0x19400000
	v_writelane_b32 v255, s2, 9
	s_addc_u32 s2, s1, 0
	v_writelane_b32 v255, s2, 11
	s_add_u32 s2, s0, 0x23600000
	v_writelane_b32 v255, s2, 13
	s_addc_u32 s2, s1, 0
	v_writelane_b32 v255, s2, 14
	s_add_u32 s2, s0, 0x27200000
	s_addc_u32 s33, s1, 0
	v_writelane_b32 v255, s2, 15
	s_add_u32 s2, s0, 0x19401880
	v_writelane_b32 v255, s2, 17
	s_addc_u32 s2, s1, 0
	v_writelane_b32 v255, s2, 18
	s_add_u32 s2, s0, 0x19401c80
	v_writelane_b32 v255, s2, 19
	s_addc_u32 s2, s1, 0
	v_writelane_b32 v255, s2, 20
	s_add_u32 s2, s0, 0x19401e80
	v_writelane_b32 v255, s2, 21
	s_addc_u32 s2, s1, 0
	v_writelane_b32 v255, s2, 22
	s_add_u32 s2, s0, 0x23600600
	v_writelane_b32 v255, s2, 23
	s_addc_u32 s2, s1, 0
	s_mov_b32 s45, s4
	s_add_u32 s4, s0, 0x19401800
	v_writelane_b32 v255, s2, 24
	s_addc_u32 s5, s1, 0
	v_writelane_b32 v255, s4, 25
	s_add_u32 s2, s0, 0x19400c00
	v_readlane_b32 s6, v253, 58
	v_writelane_b32 v255, s5, 26
	v_writelane_b32 v255, s2, 27
	s_addc_u32 s2, s1, 0
	v_writelane_b32 v255, s2, 28
	s_add_u32 s2, s0, 0x19401000
	v_writelane_b32 v255, s2, 29
	s_addc_u32 s2, s1, 0
	v_writelane_b32 v255, s2, 30
	s_add_u32 s2, s0, 0x19401200
	v_writelane_b32 v255, s2, 31
	s_addc_u32 s2, s1, 0
	v_writelane_b32 v255, s2, 32
	v_readlane_b32 s7, v253, 59
	v_readlane_b32 s4, v255, 5
	s_lshl_b32 s44, s4, 2
	s_add_u32 s2, s0, 0x19400400
	v_readlane_b32 s5, v255, 6
	v_writelane_b32 v255, s2, 33
	s_addc_u32 s2, s1, 0
	v_writelane_b32 v255, s2, 34
	s_add_u32 s0, s0, 0x19400800
	v_writelane_b32 v255, s0, 35
	s_addc_u32 s0, s1, 0
	v_writelane_b32 v255, s0, 36
	v_writelane_b32 v255, s44, 37
	v_readlane_b32 s8, v253, 60
	v_readlane_b32 s9, v253, 61
	v_writelane_b32 v255, s45, 38
	v_readlane_b32 s10, v253, 62
	v_readlane_b32 s11, v253, 63
	v_readlane_b32 s12, v254, 0
	v_readlane_b32 s13, v254, 1
	v_readlane_b32 s14, v254, 2
	v_readlane_b32 s15, v254, 3
	v_readlane_b32 s16, v254, 4
	v_readlane_b32 s17, v254, 5
	v_readlane_b32 s18, v254, 6
	v_readlane_b32 s19, v254, 7
	s_branch .LBB0_498

.LBB0_783:
	s_setprio 0
	s_waitcnt vmcnt(0)
	s_and_b64 vcc, exec, s[72:73]
	s_barrier
	s_cbranch_vccnz .LBB0_829
	v_mbcnt_lo_u32_b32 v0, -1, 0
	v_mbcnt_hi_u32_b32 v0, -1, v0
	s_nop 0
	v_cmp_eq_u32_e32 vcc, 0, v0
	s_and_saveexec_b64 s[0:1], vcc
	s_cbranch_execz .LBB0_828
	v_readlane_b32 s4, v254, 32
	s_mov_b64 s[36:37], s[82:83]
	s_mov_b32 s33, s77
	v_mov_b32_e32 v0, s4
	s_waitcnt vmcnt(0) expcnt(0) lgkmcnt(0)
	ds_read_b32 v2, v0
	v_readlane_b32 s4, v254, 33
	s_waitcnt lgkmcnt(0)
	v_cmp_ne_u32_e32 vcc, 0, v2
	v_mov_b32_e32 v0, s4
	ds_read_b32 v0, v0
	s_cbranch_vccnz .LBB0_799
	s_add_u32 s4, s36, 0x1000
	s_addc_u32 s5, s37, 0
	s_add_u32 s6, s36, 0x1100
	s_addc_u32 s7, s37, 0
	s_add_u32 s8, s36, 0x1200
	s_addc_u32 s9, s37, 0
	s_add_u32 s10, s36, 0x1300
	s_addc_u32 s11, s37, 0
	s_mov_b32 s30, 1
	s_mov_b64 s[12:13], 0
	s_branch .LBB0_789
